# in-projection: the leading wave half's realignment barrier is taken one 16-row group later in the epilogue (after its first two stores)
# speedup vs baseline: 1.0011x; 1.0011x over previous
; __device__ __forceinline__ unsigned cvt_pk_bf16(float lo, float hi) { unsigned r; asm volatile("v_cvt_pk_bf16_f32 %0, %1, %2" : "=v"(r) : "v"(lo), "v"(hi)); return r; }
; #define PG8_BAR __builtin_amdgcn_s_barrier()
;     __device__ __forceinline__ void operator()(const f32x4 (&acc)[2][2][4][2], const Unit& u, int wr, int wc, int fr, int fq) const {
;         const int row0 = u.pm * BM + wr * 64 + fr; const bool second = split > 0 && u.pn >= split; const int col0 = (second ? u.pn - split : u.pn) * BM + wc * 32 + 8 * fq;
;         bf16_t* const Ob = second ? O2 : O; const int ld = second ? ldc2 : ldc;
; #pragma unroll
;         for (int ai = 0; ai < 2; ++ai)
; #pragma unroll
;             for (int m = 0; m < 4; ++m) { bf16_t* rowp = Ob + (size_t)(row0 + ai * HALF + m * 16) * ld + col0;
;                 float rs = 1.f; if (ss) rs = __builtin_amdgcn_rsqf((float)ss[row0 + ai * HALF + m * 16] * (1.f / (2048.f * 262144.f)) + 1e-6f);
; #pragma unroll
;                 for (int bj = 0; bj < 2; ++bj) { const f32x4 v0 = acc[ai][bj][m][0] * rs, v1 = acc[ai][bj][m][1] * rs;
;                     u32x4 w; w.x = cvt_pk_bf16(v0[0], v0[1]); w.y = cvt_pk_bf16(v0[2], v0[3]); w.z = cvt_pk_bf16(v1[0], v1[1]); w.w = cvt_pk_bf16(v1[2], v1[3]);
;                     *(u32x4*)(rowp + bj * HALF) = w; } }
; template <class Epi, class Sched, bool ALIGN_EPI = false, bool SP2 = false>
; __device__ __forceinline__ void gemm_phase(PG8_LAS unsigned char* lds, const Gemm g, const Sched& S, const Epi& E) {
;     ...
;         if constexpr (ALIGN_EPI) { if (wr == 0) PG8_BAR; }
.LBB0_564:
	s_cmp_gt_i32 s16, 8
	s_cselect_b32 s11, -9, 0
	s_movk_i32 s10, 0x900
	s_cselect_b32 s23, s81, s2
	s_cselect_b32 s37, s80, s1
	s_cselect_b32 s10, 0x1080, s10
	s_add_i32 s11, s11, s16
	v_lshl_or_b32 v144, s11, 8, v150
	v_mov_b32_e32 v152, s37
	v_mov_b32_e32 v153, s23
	v_ashrrev_i32_e32 v145, 31, v144
	v_lshl_add_u64 v[144:145], v[144:145], 1, v[152:153]
	v_mad_i64_i32 v[152:153], s[50:51], s10, v140, 0
	v_lshl_add_u64 v[152:153], v[152:153], 1, v[144:145]
	v_pk_mul_f32 v[128:129], v[128:129], v[148:149] op_sel_hi:[1,0]
	v_pk_mul_f32 v[126:127], v[126:127], v[148:149] op_sel_hi:[1,0]
	v_pk_mul_f32 v[154:155], v[124:125], v[148:149] op_sel_hi:[1,0]
	v_pk_mul_f32 v[124:125], v[122:123], v[148:149] op_sel_hi:[1,0]
	v_cvt_pk_bf16_f32 v122, v126, v127
	v_cvt_pk_bf16_f32 v123, v128, v129
	s_and_b64 vcc, exec, s[42:43]
	v_cvt_pk_bf16_f32 v124, v124, v125
	v_cvt_pk_bf16_f32 v125, v154, v155
	global_store_dwordx4 v[152:153], v[122:125], off
	v_pk_mul_f32 v[120:121], v[120:121], v[148:149] op_sel_hi:[1,0]
	v_pk_mul_f32 v[118:119], v[118:119], v[148:149] op_sel_hi:[1,0]
	v_pk_mul_f32 v[122:123], v[116:117], v[148:149] op_sel_hi:[1,0]
	v_pk_mul_f32 v[116:117], v[114:115], v[148:149] op_sel_hi:[1,0]
	v_cvt_pk_bf16_f32 v114, v118, v119
	v_cvt_pk_bf16_f32 v115, v120, v121
	s_nop 0
	v_cvt_pk_bf16_f32 v116, v116, v117
	v_cvt_pk_bf16_f32 v117, v122, v123
	global_store_dwordx4 v[152:153], v[114:117], off offset:256
	s_cbranch_vccnz .LBB0_566
	s_nop 0
	v_mov_b32_e32 v114, v162
	v_mov_b32_e32 v115, v163
	v_ffbh_u32_e32 v116, v115
	v_min_u32_e32 v116, 32, v116
	v_lshlrev_b64 v[114:115], v116, v[114:115]
	v_min_u32_e32 v114, 1, v114
	v_or_b32_e32 v114, v115, v114
	v_cvt_f32_u32_e32 v114, v114
	v_sub_u32_e32 v115, 32, v116
	v_ldexp_f32 v114, v114, v115
	v_fmamk_f32 v114, v114, 0x31000000, v232
	v_rsq_f32_e32 v146, v114
.LBB0_566:
	s_and_b64 vcc, exec, s[14:15]
	s_cbranch_vccz .Lalign_proj
	s_barrier
.Lalign_proj:
	s_nop 0
	v_or_b32_e32 v114, 16, v140
	v_mad_i64_i32 v[114:115], s[50:51], s10, v114, 0
	v_lshl_add_u64 v[114:115], v[114:115], 1, v[144:145]
	v_pk_mul_f32 v[112:113], v[112:113], v[146:147] op_sel_hi:[1,0]
	v_pk_mul_f32 v[110:111], v[110:111], v[146:147] op_sel_hi:[1,0]
	v_pk_mul_f32 v[116:117], v[108:109], v[146:147] op_sel_hi:[1,0]
	v_pk_mul_f32 v[108:109], v[106:107], v[146:147] op_sel_hi:[1,0]
	v_cvt_pk_bf16_f32 v106, v110, v111
	v_cvt_pk_bf16_f32 v107, v112, v113
	v_pk_mul_f32 v[104:105], v[104:105], v[146:147] op_sel_hi:[1,0]
	v_cvt_pk_bf16_f32 v108, v108, v109
	v_cvt_pk_bf16_f32 v109, v116, v117
	global_store_dwordx4 v[114:115], v[106:109], off
	v_pk_mul_f32 v[102:103], v[102:103], v[146:147] op_sel_hi:[1,0]
	s_and_b64 vcc, exec, s[42:43]
	v_pk_mul_f32 v[106:107], v[100:101], v[146:147] op_sel_hi:[1,0]
	v_pk_mul_f32 v[100:101], v[98:99], v[146:147] op_sel_hi:[1,0]
	v_cvt_pk_bf16_f32 v98, v102, v103
	v_cvt_pk_bf16_f32 v99, v104, v105
	s_nop 0
	v_cvt_pk_bf16_f32 v100, v100, v101
	v_cvt_pk_bf16_f32 v101, v106, v107
	global_store_dwordx4 v[114:115], v[98:101], off offset:256
	s_nop 1
	v_mov_b32_e32 v98, 1.0
	v_mov_b32_e32 v100, 1.0
	s_cbranch_vccnz .LBB0_568
	s_nop 0
	v_mov_b32_e32 v100, v164
	v_mov_b32_e32 v101, v165
	v_ffbh_u32_e32 v99, v101
	v_min_u32_e32 v99, 32, v99
	v_lshlrev_b64 v[100:101], v99, v[100:101]
	v_min_u32_e32 v100, 1, v100
	v_or_b32_e32 v100, v101, v100
	v_cvt_f32_u32_e32 v100, v100
	v_sub_u32_e32 v99, 32, v99
	v_ldexp_f32 v99, v100, v99
	v_fmamk_f32 v99, v99, 0x31000000, v232
	v_rsq_f32_e32 v100, v99
